# write-through dwordx4 stores + forgetting-attention loop: deferred gate-bias wait via AGPR and wide done-flag reads + v_permlane32_swap for the row-max exchange in MLA and forgetting attention
# speedup vs baseline: 1.0103x; 1.0103x over previous
; __device__ __forceinline__ float fexp2(float x) { return __builtin_amdgcn_exp2f(x); }
; template <int DV>
; __device__ __forceinline__ void tile_pv(const LAS unsigned char* Vt, f32x16& s0, f32x16& s1, f32x16 (&o)[DV / 32], float& m, float& l, int lane) {
;     ...
;     float mx = s0[0];
; #pragma unroll
;     for (int r = 0; r < 16; ++r) { mx = fmaxf(mx, s0[r]); mx = fmaxf(mx, s1[r]); }
;     mx = fmaxf(mx, __shfl_xor(mx, 32));
;     if (__any(mx > m + 4.0f)) {
;         const float mnew = fmaxf(m, mx);
;         const float alpha = fexp2(m - mnew);
;         m = mnew; l *= alpha;
; #pragma unroll
;         for (int db = 0; db < DV / 32; ++db)
; #pragma unroll
;             for (int r = 0; r < 16; ++r) o[db][r] *= alpha;
;     }
.LBB0_991:
	s_nop 10
	v_max_f32_e32 v0, v66, v66
	v_max_f32_e32 v220, v82, v82
	v_max_f32_e32 v0, v220, v0
	v_max3_f32 v0, v0, v83, v67
	v_max3_f32 v0, v0, v84, v68
	v_max3_f32 v0, v0, v85, v69
	v_max3_f32 v0, v0, v86, v70
	v_max3_f32 v0, v0, v87, v71
	v_max3_f32 v0, v0, v88, v72
	v_max3_f32 v0, v0, v89, v73
	v_max3_f32 v0, v0, v90, v74
	v_max3_f32 v0, v0, v91, v75
	v_max3_f32 v0, v0, v92, v76
	v_max3_f32 v0, v0, v93, v77
	v_and_b32_e32 v221, 64, v217
	v_max3_f32 v0, v0, v94, v78
	v_xor_b32_e32 v220, 32, v217
	v_add_u32_e32 v221, 64, v221
	v_max3_f32 v0, v0, v95, v79
	v_cmp_lt_i32_e32 vcc, v220, v221
	v_max3_f32 v0, v0, v96, v80
	v_max3_f32 v0, v0, v97, v81
	v_cndmask_b32_e32 v220, v217, v220, vcc
	v_lshlrev_b32_e32 v220, 2, v220
	v_mov_b32_e32 v221, v0
	s_nop 1
	v_permlane32_swap_b32_e32 v221, v0
	s_waitcnt lgkmcnt(0)
	v_max_f32_e32 v221, v221, v221
	v_max_f32_e32 v0, v0, v221
	v_add_f32_e32 v221, 4.0, v219
	v_cmp_gt_f32_e32 vcc, v0, v221
	s_cbranch_vccz .LBB0_993
	v_max_f32_e32 v0, v0, v0
	v_max_f32_e32 v221, v219, v219
	v_max_f32_e32 v221, v221, v0
	v_sub_f32_e32 v0, v219, v221
	v_exp_f32_e32 v0, v0
	v_mov_b32_e32 v219, v221
	v_mul_f32_e32 v218, v218, v0
	v_pk_mul_f32 v[64:65], v[64:65], v[0:1] op_sel_hi:[1,0]
	v_pk_mul_f32 v[62:63], v[62:63], v[0:1] op_sel_hi:[1,0]
	v_pk_mul_f32 v[60:61], v[60:61], v[0:1] op_sel_hi:[1,0]
	v_pk_mul_f32 v[58:59], v[58:59], v[0:1] op_sel_hi:[1,0]
	v_pk_mul_f32 v[56:57], v[56:57], v[0:1] op_sel_hi:[1,0]
	v_pk_mul_f32 v[54:55], v[54:55], v[0:1] op_sel_hi:[1,0]
	v_pk_mul_f32 v[52:53], v[52:53], v[0:1] op_sel_hi:[1,0]
	v_pk_mul_f32 v[50:51], v[50:51], v[0:1] op_sel_hi:[1,0]
	v_pk_mul_f32 v[48:49], v[48:49], v[0:1] op_sel_hi:[1,0]
	v_pk_mul_f32 v[46:47], v[46:47], v[0:1] op_sel_hi:[1,0]
	v_pk_mul_f32 v[44:45], v[44:45], v[0:1] op_sel_hi:[1,0]
	v_pk_mul_f32 v[42:43], v[42:43], v[0:1] op_sel_hi:[1,0]
	v_pk_mul_f32 v[40:41], v[40:41], v[0:1] op_sel_hi:[1,0]
	v_pk_mul_f32 v[38:39], v[38:39], v[0:1] op_sel_hi:[1,0]
	v_pk_mul_f32 v[36:37], v[36:37], v[0:1] op_sel_hi:[1,0]
	v_pk_mul_f32 v[34:35], v[34:35], v[0:1] op_sel_hi:[1,0]
	v_pk_mul_f32 v[32:33], v[32:33], v[0:1] op_sel_hi:[1,0]
	v_pk_mul_f32 v[30:31], v[30:31], v[0:1] op_sel_hi:[1,0]
	v_pk_mul_f32 v[28:29], v[28:29], v[0:1] op_sel_hi:[1,0]
	v_pk_mul_f32 v[26:27], v[26:27], v[0:1] op_sel_hi:[1,0]
	v_pk_mul_f32 v[24:25], v[24:25], v[0:1] op_sel_hi:[1,0]
	v_pk_mul_f32 v[22:23], v[22:23], v[0:1] op_sel_hi:[1,0]
	v_pk_mul_f32 v[20:21], v[20:21], v[0:1] op_sel_hi:[1,0]
	v_pk_mul_f32 v[18:19], v[18:19], v[0:1] op_sel_hi:[1,0]
	v_pk_mul_f32 v[16:17], v[16:17], v[0:1] op_sel_hi:[1,0]
	v_pk_mul_f32 v[14:15], v[14:15], v[0:1] op_sel_hi:[1,0]
	v_pk_mul_f32 v[12:13], v[12:13], v[0:1] op_sel_hi:[1,0]
	v_pk_mul_f32 v[10:11], v[10:11], v[0:1] op_sel_hi:[1,0]
	v_pk_mul_f32 v[8:9], v[8:9], v[0:1] op_sel_hi:[1,0]
	v_pk_mul_f32 v[6:7], v[6:7], v[0:1] op_sel_hi:[1,0]
	v_pk_mul_f32 v[4:5], v[4:5], v[0:1] op_sel_hi:[1,0]
	v_pk_mul_f32 v[2:3], v[2:3], v[0:1] op_sel_hi:[1,0]

; template <int DQK, bool FOX>
; __device__ __forceinline__ void causal_attn_phase(LAS unsigned char* lds, const bf16_t* Q, int qpitch, const bf16_t* K1, const bf16_t* K2, const bf16_t* V, bf16_t* O, const float* cum2, const float* rope_cs_tab, const float* fox_ct) {
;     ...
;                 int alld = 1;
; #pragma unroll
;                 for (int w_ = 0; w_ < 8; ++w_) alld &= dflag[(tt & 1) * 8 + w_];
;                 if (alld) break;
.LBB0_2754:
	s_lshl_b32 s8, s49, 5
	s_add_i32 s8, s8, 0
	s_add_i32 s8, s8, 0x12c20
	v_mov_b32_e32 v0, s8
	s_waitcnt lgkmcnt(0)
	s_barrier
	ds_read_b128 v[66:69], v0
	ds_read_b128 v[70:73], v0 offset:16
	s_cmp_lt_u32 s87, s38
	s_cselect_b64 s[8:9], -1, 0
	s_add_i32 s87, s87, 1
	s_sub_i32 s47, s47, 64
	s_add_i32 s48, s48, -4
	s_add_i32 s24, s24, -1
	v_add_u32_e32 v230, 64, v230
	s_waitcnt lgkmcnt(0)
	v_and_b32_e32 v66, v66, v67
	v_and_b32_e32 v68, v68, v69
	v_and_b32_e32 v70, v70, v71
	v_and_b32_e32 v72, v72, v73
	v_and_b32_e32 v66, v66, v68
	v_and_b32_e32 v70, v70, v72
	v_and_b32_e32 v0, v66, v70
	v_and_b32_e32 v0, 1, v0
	v_cmp_eq_u32_e32 vcc, 0, v0
	s_and_b64 s[8:9], vcc, s[8:9]
	s_and_b64 vcc, exec, s[8:9]
	s_cbranch_vccz .LBB0_2743
.LBB0_2755:
	s_add_i32 s8, s24, 1
	s_cmp_gt_i32 s8, 0
	s_cselect_b64 s[36:37], -1, 0
	s_cmp_lt_i32 s8, 1
	s_cbranch_scc1 .LBB0_2759
	s_lshl_b64 s[8:9], s[24:25], 18
	s_add_u32 s10, s3, s8
	s_addc_u32 s11, s33, s9
	s_add_u32 s8, s39, s8
	v_lshl_add_u64 v[66:67], v[178:179], 1, s[10:11]
	s_addc_u32 s9, s86, s9
	v_lshl_add_u64 v[68:69], v[180:181], 1, s[10:11]
	global_load_dwordx4 v[160:163], v[66:67], off
	global_load_dwordx4 v[164:167], v[68:69], off
	v_lshl_add_u64 v[66:67], v[182:183], 1, s[8:9]
	v_lshl_add_u64 v[68:69], v[184:185], 1, s[8:9]
	global_load_dwordx4 v[168:171], v[66:67], off
	global_load_dwordx4 v[172:175], v[68:69], off
	s_and_saveexec_b64 s[8:9], s[44:45]
	s_cbranch_execz .LBB0_2758
	v_add_u32_e32 v66, s47, v228
	v_ashrrev_i32_e32 v67, 31, v66
	v_lshl_add_u64 v[66:67], v[66:67], 2, s[0:1]
	global_load_dword a0, v[66:67], off
	v_mov_b32_e32 v66, s48
	ds_read_b32 a1, v66

; __device__ __forceinline__ float fexp2(float x) { return __builtin_amdgcn_exp2f(x); }
; template <int DV>
; __device__ __forceinline__ void tile_pv(const LAS unsigned char* Vt, f32x16& s0, f32x16& s1, f32x16 (&o)[DV / 32], float& m, float& l, int lane) {
;     ...
;     float mx = s0[0];
; #pragma unroll
;     for (int r = 0; r < 16; ++r) { mx = fmaxf(mx, s0[r]); mx = fmaxf(mx, s1[r]); }
;     mx = fmaxf(mx, __shfl_xor(mx, 32));
;     if (__any(mx > m + 4.0f)) {
;         const float mnew = fmaxf(m, mx);
;         const float alpha = fexp2(m - mnew);
;         m = mnew; l *= alpha;
; #pragma unroll
;         for (int db = 0; db < DV / 32; ++db)
; #pragma unroll
;             for (int r = 0; r < 16; ++r) o[db][r] *= alpha;
;     }
.LBB0_2766:
	v_max_f32_e32 v96, v94, v94
	v_max_f32_e32 v98, v0, v0
	v_max_f32_e32 v96, v98, v96
	v_max3_f32 v96, v96, v95, v97
	v_max3_f32 v96, v96, v90, v92
	v_max3_f32 v96, v96, v91, v93
	v_max3_f32 v96, v96, v86, v88
	v_max3_f32 v96, v96, v87, v89
	v_max3_f32 v96, v96, v82, v84
	v_max3_f32 v96, v96, v83, v85
	v_max3_f32 v96, v96, v78, v80
	v_max3_f32 v96, v96, v79, v81
	v_max3_f32 v96, v96, v74, v76
	v_max3_f32 v96, v96, v75, v77
	v_max3_f32 v96, v96, v68, v72
	v_max3_f32 v96, v96, v69, v73
	v_max3_f32 v96, v96, v66, v70
	v_max3_f32 v96, v96, v67, v71
	v_mov_b32_e32 v98, v96
	s_nop 1
	v_permlane32_swap_b32_e32 v98, v96
	s_waitcnt lgkmcnt(0)
	v_max_f32_e32 v98, v98, v98
	v_max_f32_e32 v96, v96, v98
	v_add_f32_e32 v98, 4.0, v231
	v_cmp_gt_f32_e32 vcc, v96, v98
	s_cbranch_vccz .LBB0_2768
	v_max_f32_e32 v96, v96, v96
	v_max_f32_e32 v98, v231, v231
	v_max_f32_e32 v98, v98, v96
	v_sub_f32_e32 v96, v231, v98
	v_exp_f32_e32 v96, v96
	v_mov_b32_e32 v231, v98
	v_mul_f32_e32 v229, v229, v96
	v_pk_mul_f32 v[64:65], v[64:65], v[96:97] op_sel_hi:[1,0]
	v_pk_mul_f32 v[62:63], v[62:63], v[96:97] op_sel_hi:[1,0]
	v_pk_mul_f32 v[60:61], v[60:61], v[96:97] op_sel_hi:[1,0]
	v_pk_mul_f32 v[58:59], v[58:59], v[96:97] op_sel_hi:[1,0]
	v_pk_mul_f32 v[56:57], v[56:57], v[96:97] op_sel_hi:[1,0]
	v_pk_mul_f32 v[54:55], v[54:55], v[96:97] op_sel_hi:[1,0]
	v_pk_mul_f32 v[52:53], v[52:53], v[96:97] op_sel_hi:[1,0]
	v_pk_mul_f32 v[50:51], v[50:51], v[96:97] op_sel_hi:[1,0]
	v_pk_mul_f32 v[48:49], v[48:49], v[96:97] op_sel_hi:[1,0]
	v_pk_mul_f32 v[46:47], v[46:47], v[96:97] op_sel_hi:[1,0]
	v_pk_mul_f32 v[44:45], v[44:45], v[96:97] op_sel_hi:[1,0]
	v_pk_mul_f32 v[42:43], v[42:43], v[96:97] op_sel_hi:[1,0]
	v_pk_mul_f32 v[40:41], v[40:41], v[96:97] op_sel_hi:[1,0]
	v_pk_mul_f32 v[38:39], v[38:39], v[96:97] op_sel_hi:[1,0]
	v_pk_mul_f32 v[36:37], v[36:37], v[96:97] op_sel_hi:[1,0]
	v_pk_mul_f32 v[34:35], v[34:35], v[96:97] op_sel_hi:[1,0]
	v_pk_mul_f32 v[32:33], v[32:33], v[96:97] op_sel_hi:[1,0]
	v_pk_mul_f32 v[30:31], v[30:31], v[96:97] op_sel_hi:[1,0]
	v_pk_mul_f32 v[28:29], v[28:29], v[96:97] op_sel_hi:[1,0]
	v_pk_mul_f32 v[26:27], v[26:27], v[96:97] op_sel_hi:[1,0]
	v_pk_mul_f32 v[24:25], v[24:25], v[96:97] op_sel_hi:[1,0]
	v_pk_mul_f32 v[22:23], v[22:23], v[96:97] op_sel_hi:[1,0]
	v_pk_mul_f32 v[20:21], v[20:21], v[96:97] op_sel_hi:[1,0]
	v_pk_mul_f32 v[18:19], v[18:19], v[96:97] op_sel_hi:[1,0]
	v_pk_mul_f32 v[16:17], v[16:17], v[96:97] op_sel_hi:[1,0]
	v_pk_mul_f32 v[14:15], v[14:15], v[96:97] op_sel_hi:[1,0]
	v_pk_mul_f32 v[12:13], v[12:13], v[96:97] op_sel_hi:[1,0]
	v_pk_mul_f32 v[10:11], v[10:11], v[96:97] op_sel_hi:[1,0]
	v_pk_mul_f32 v[8:9], v[8:9], v[96:97] op_sel_hi:[1,0]
	v_pk_mul_f32 v[6:7], v[6:7], v[96:97] op_sel_hi:[1,0]
	v_pk_mul_f32 v[4:5], v[4:5], v[96:97] op_sel_hi:[1,0]
	v_pk_mul_f32 v[2:3], v[2:3], v[96:97] op_sel_hi:[1,0]

; template <int DQK, bool FOX>
; __device__ __forceinline__ void causal_attn_phase(LAS unsigned char* lds, const bf16_t* Q, int qpitch, const bf16_t* K1, const bf16_t* K2, const bf16_t* V, bf16_t* O, const float* cum2, const float* rope_cs_tab, const float* fox_ct) {
;     ...
;                 if (lane == 0) dflag[(tt & 1) * 8 + wid] = done ? 1 : 0;
;                 if (t > 0) CA_LSTORE((tt + 1) & 1);
.LBB0_2769:
	s_and_saveexec_b64 s[8:9], s[6:7]
	s_lshl_b32 s10, s49, 5
	s_add_i32 s10, s41, s10
	v_cndmask_b32_e64 v0, 0, 1, s[4:5]
	v_mov_b32_e32 v66, s10
	ds_write_b32 v66, v0
	s_or_b64 exec, exec, s[8:9]
	s_andn2_b64 vcc, exec, s[36:37]
	s_cbranch_vccnz .LBB0_2754
	s_xor_b32 s8, s49, 1
	s_mul_i32 s8, s8, 0x9500
	s_add_i32 s10, s8, 0
	v_add3_u32 v0, s10, v217, v218
	s_waitcnt vmcnt(3)
	ds_write_b128 v0, v[160:163]
	v_add3_u32 v0, s10, v219, v220
	s_waitcnt vmcnt(2)
	ds_write_b128 v0, v[164:167]
	v_add_u32_e32 v0, s10, v196
	v_add_u32_e32 v66, v0, v221
	v_add_u32_e32 v0, v0, v222
	s_waitcnt vmcnt(1)
	ds_write_b128 v66, v[168:171] offset:17408
	s_waitcnt vmcnt(0)
	ds_write_b128 v0, v[172:175] offset:17408
	s_and_saveexec_b64 s[8:9], s[44:45]
	s_cbranch_execz .LBB0_2753
	v_add_u32_e32 v0, s10, v198
	s_waitcnt lgkmcnt(0)
	v_accvgpr_read_b32 v66, a0
	v_accvgpr_read_b32 v67, a1
	s_nop 0
	v_add_f32_e32 v66, v66, v67
	v_mul_f32_e32 v187, 0x3fb8aa3b, v66
	ds_write_b32 v0, v187 offset:37888
	s_branch .LBB0_2753

; #define LAS __attribute__((address_space(3)))
; __global__ void __launch_bounds__(512) mega_fwd(Params p_unused) {
;     extern __shared__ __attribute__((aligned(16))) unsigned char lds_raw[];
;     LAS unsigned char* lds = (LAS unsigned char*)lds_raw;
	.amdhsa_kernel _Z8mega_fwd6Params
		.amdhsa_group_segment_fixed_size 0
		.amdhsa_private_segment_fixed_size 0
		.amdhsa_kernarg_size 480
		.amdhsa_user_sgpr_count 2
		.amdhsa_user_sgpr_dispatch_ptr 0
		.amdhsa_user_sgpr_queue_ptr 0
		.amdhsa_user_sgpr_kernarg_segment_ptr 1
		.amdhsa_user_sgpr_dispatch_id 0
		.amdhsa_user_sgpr_kernarg_preload_length 0
		.amdhsa_user_sgpr_kernarg_preload_offset 0
		.amdhsa_user_sgpr_private_segment_size 0
		.amdhsa_uses_dynamic_stack 0
		.amdhsa_enable_private_segment 0
		.amdhsa_system_sgpr_workgroup_id_x 1
		.amdhsa_system_sgpr_workgroup_id_y 0
		.amdhsa_system_sgpr_workgroup_id_z 0
		.amdhsa_system_sgpr_workgroup_info 0
		.amdhsa_system_vgpr_workitem_id 2
		.amdhsa_next_free_vgpr 250
		.amdhsa_next_free_sgpr 98
		.amdhsa_accum_offset 248
		.amdhsa_reserve_vcc 1
		.amdhsa_float_round_mode_32 0
		.amdhsa_float_round_mode_16_64 0
		.amdhsa_float_denorm_mode_32 3
		.amdhsa_float_denorm_mode_16_64 3
		.amdhsa_dx10_clamp 1
		.amdhsa_ieee_mode 1
		.amdhsa_fp16_overflow 0
		.amdhsa_tg_split 0
		.amdhsa_exception_fp_ieee_invalid_op 0
		.amdhsa_exception_fp_denorm_src 0
		.amdhsa_exception_fp_ieee_div_zero 0
		.amdhsa_exception_fp_ieee_overflow 0
		.amdhsa_exception_fp_ieee_underflow 0
		.amdhsa_exception_fp_ieee_inexact 0
		.amdhsa_exception_int_div_zero 0
	.end_amdhsa_kernel
